# v86 with the late-scan prefetch window moved to intervals 52-62 (closer to the phase end)
# baseline (speedup 1.0000x reference)
.Lcv_noitem:
	s_sub_u32 s54, s12, 52
	s_cmp_lt_u32 s54, 11
	s_cbranch_scc0 .Lpf_skip
	s_lshl_b32 s54, s54, 10
	s_lshl_b32 s53, s8, 2
	s_add_i32 s53, s53, s11
	s_add_i32 s53, s53, -4
	s_add_i32 s54, s54, s53
	s_cmp_lt_u32 s54, 0x2b04
	s_cbranch_scc0 .Lpf_skip
	s_cmp_lt_u32 s54, 0x2080
	s_cbranch_scc0 .Lpf_win
	s_lshl_b32 s55, s54, 12
	s_add_u32 s56, s84, s55
	s_addc_u32 s57, s85, 0
	s_branch .Lpf_go
